# grid-barrier / flag polls without back-off: s_sleep 1 -> s_sleep 0 at all 73 spin sites, on top of v25
# speedup vs baseline: 1.0044x; 1.0044x over previous
; __device__ __forceinline__ unsigned xb_ld(unsigned* p)              { return __hip_atomic_load(p, __ATOMIC_RELAXED, __HIP_MEMORY_SCOPE_AGENT); }
; __device__ __forceinline__ void xcd_barrier_complete(unsigned* bar, unsigned x, unsigned& nloc, unsigned& nx) {
;     const unsigned G = gridDim.x * gridDim.y * gridDim.z;
;     unsigned sum, cnt, mine, sp = 0u;
;     for (;;) {
;         sum = 0u; cnt = 0u; mine = 0u;
; #pragma unroll
;         for (unsigned j = 0; j < 16; ++j) { const unsigned c = xb_ld(&bar[XB_XCNT(j)]); sum += c; cnt += (c > 0u) ? 1u : 0u; mine = (j == x) ? c : mine; }
;         if (sum == G) break;
;         __builtin_amdgcn_s_sleep(1);
;         if ((++sp & 255u) == 0u) { if (xb_ld(&bar[XB_TMO])) break; if (sp > XB_SPIN_CAP) { atomicAdd(&bar[XB_TMO], 1u); break; } }
;     }
;     nloc = mine > 0u ? mine : 1u; nx = cnt > 0u ? cnt : 1u;
; }
.LBB0_68:
	global_load_dword v17, v18, s[34:35] offset:1024 sc1
	global_load_dword v2, v18, s[34:35] offset:1280 sc1
	global_load_dword v3, v18, s[34:35] offset:1536 sc1
	global_load_dword v4, v18, s[34:35] offset:1792 sc1
	global_load_dword v5, v18, s[34:35] offset:2048 sc1
	global_load_dword v6, v18, s[34:35] offset:2304 sc1
	global_load_dword v7, v18, s[34:35] offset:2560 sc1
	global_load_dword v8, v18, s[34:35] offset:2816 sc1
	global_load_dword v9, v18, s[34:35] offset:3072 sc1
	global_load_dword v10, v18, s[34:35] offset:3328 sc1
	global_load_dword v11, v18, s[34:35] offset:3584 sc1
	global_load_dword v12, v18, s[34:35] offset:3840 sc1
	global_load_dword v13, v18, s[2:3] sc1
	global_load_dword v14, v18, s[4:5] sc1
	global_load_dword v15, v18, s[6:7] sc1
	global_load_dword v16, v18, s[8:9] sc1
	s_mov_b64 s[10:11], -1
	s_mov_b64 s[12:13], -1
	s_waitcnt vmcnt(14)
	v_add_u32_e32 v19, v2, v17
	s_waitcnt vmcnt(13)
	v_add_u32_e32 v19, v19, v3
	s_waitcnt vmcnt(12)
	v_add_u32_e32 v19, v19, v4
	s_waitcnt vmcnt(11)
	v_add_u32_e32 v19, v19, v5
	s_waitcnt vmcnt(10)
	v_add_u32_e32 v19, v19, v6
	s_waitcnt vmcnt(9)
	v_add_u32_e32 v19, v19, v7
	s_waitcnt vmcnt(8)
	v_add_u32_e32 v19, v19, v8
	s_waitcnt vmcnt(7)
	v_add_u32_e32 v19, v19, v9
	s_waitcnt vmcnt(6)
	v_add_u32_e32 v19, v19, v10
	s_waitcnt vmcnt(5)
	v_add_u32_e32 v19, v19, v11
	s_waitcnt vmcnt(4)
	v_add_u32_e32 v19, v19, v12
	s_waitcnt vmcnt(3)
	v_add_u32_e32 v19, v19, v13
	s_waitcnt vmcnt(2)
	v_add_u32_e32 v19, v19, v14
	s_waitcnt vmcnt(1)
	v_add_u32_e32 v19, v19, v15
	s_waitcnt vmcnt(0)
	v_add_u32_e32 v19, v19, v16
	v_cmp_eq_u32_e32 vcc, s24, v19
	s_cbranch_vccnz .LBB0_67
	s_and_b32 s10, s25, 0xff
	s_cmp_eq_u32 s10, 0
	s_mov_b64 s[10:11], -1
	s_mov_b64 s[22:23], -1
	s_sleep 0
	s_cbranch_scc1 .LBB0_72
	s_and_b64 vcc, exec, s[22:23]
	s_cbranch_vccz .LBB0_67

; __device__ __forceinline__ unsigned xb_ld(unsigned* p)              { return __hip_atomic_load(p, __ATOMIC_RELAXED, __HIP_MEMORY_SCOPE_AGENT); }
; __device__ __forceinline__ unsigned xb_add(unsigned* p, unsigned v) { return __hip_atomic_fetch_add(p, v, __ATOMIC_RELAXED, __HIP_MEMORY_SCOPE_AGENT); }
; #define XB_SPIN(cond, bar) do { unsigned _sp = 0; while (cond) { __builtin_amdgcn_s_sleep(1); \
;     if ((++_sp & 255u) == 0u) { if (xb_ld(&(bar)[XB_TMO])) break; if (_sp > XB_SPIN_CAP) { atomicAdd(&(bar)[XB_TMO], 1u); break; } } } } while (0)
; __device__ __forceinline__ void xcd_barrier(const XcdBarrier& b) {
;     ...
;             const unsigned og = xb_add(&bar[XB_TOP], 1u);
;             const unsigned tg = og / nx;
;             if (og + 1u == (tg + 1u) * nx) xb_add(&bar[XB_TOPGEN], 1u);
;             else XB_SPIN(xb_ld(&bar[XB_TOPGEN]) == tg, bar);
;             __builtin_amdgcn_fence(__ATOMIC_ACQUIRE, "agent");
;             xb_add(&bar[XB_XGEN(b.x)], 1u);
;             asm volatile("s_waitcnt vmcnt(0)" ::: "memory");
;         } else {
;             XB_SPIN(xb_ld(&bar[XB_XGEN(b.x)]) == gen, bar);
.LBB0_86:
	s_and_b32 s24, s26, 0xff
	s_mov_b64 s[22:23], -1
	s_cmp_lg_u32 s24, 0
	s_mov_b64 s[38:39], -1
	s_sleep 0
	s_cbranch_scc0 .LBB0_89
	s_and_b64 vcc, exec, s[38:39]
	s_cbranch_vccz .LBB0_85

; __device__ __forceinline__ unsigned xb_ld(unsigned* p)              { return __hip_atomic_load(p, __ATOMIC_RELAXED, __HIP_MEMORY_SCOPE_AGENT); }
; __device__ __forceinline__ unsigned xb_add(unsigned* p, unsigned v) { return __hip_atomic_fetch_add(p, v, __ATOMIC_RELAXED, __HIP_MEMORY_SCOPE_AGENT); }
; #define XB_SPIN(cond, bar) do { unsigned _sp = 0; while (cond) { __builtin_amdgcn_s_sleep(1); \
;     if ((++_sp & 255u) == 0u) { if (xb_ld(&(bar)[XB_TMO])) break; if (_sp > XB_SPIN_CAP) { atomicAdd(&(bar)[XB_TMO], 1u); break; } } } } while (0)
; __device__ __forceinline__ void xcd_barrier(const XcdBarrier& b) {
;     ...
;             const unsigned og = xb_add(&bar[XB_TOP], 1u);
;             const unsigned tg = og / nx;
;             if (og + 1u == (tg + 1u) * nx) xb_add(&bar[XB_TOPGEN], 1u);
;             else XB_SPIN(xb_ld(&bar[XB_TOPGEN]) == tg, bar);
;             __builtin_amdgcn_fence(__ATOMIC_ACQUIRE, "agent");
;             xb_add(&bar[XB_XGEN(b.x)], 1u);
;             asm volatile("s_waitcnt vmcnt(0)" ::: "memory");
;         } else {
;             XB_SPIN(xb_ld(&bar[XB_XGEN(b.x)]) == gen, bar);
.LBB0_103:
	s_and_b32 s24, s26, 0xff
	s_cmp_lg_u32 s24, 0
	s_mov_b64 s[38:39], -1
	s_sleep 0
	s_cbranch_scc0 .LBB0_106
	s_mov_b64 s[42:43], -1
	s_and_b64 vcc, exec, s[38:39]
	s_cbranch_vccz .LBB0_102

; __device__ __forceinline__ unsigned xb_ld(unsigned* p)              { return __hip_atomic_load(p, __ATOMIC_RELAXED, __HIP_MEMORY_SCOPE_AGENT); }
; __device__ __forceinline__ unsigned xb_add(unsigned* p, unsigned v) { return __hip_atomic_fetch_add(p, v, __ATOMIC_RELAXED, __HIP_MEMORY_SCOPE_AGENT); }
; #define XB_SPIN(cond, bar) do { unsigned _sp = 0; while (cond) { __builtin_amdgcn_s_sleep(1); \
;     if ((++_sp & 255u) == 0u) { if (xb_ld(&(bar)[XB_TMO])) break; if (_sp > XB_SPIN_CAP) { atomicAdd(&(bar)[XB_TMO], 1u); break; } } } } while (0)
; __device__ __forceinline__ void xcd_barrier(const XcdBarrier& b) {
;     ...
;             const unsigned og = xb_add(&bar[XB_TOP], 1u);
;             const unsigned tg = og / nx;
;             if (og + 1u == (tg + 1u) * nx) xb_add(&bar[XB_TOPGEN], 1u);
;             else XB_SPIN(xb_ld(&bar[XB_TOPGEN]) == tg, bar);
;             __builtin_amdgcn_fence(__ATOMIC_ACQUIRE, "agent");
;             xb_add(&bar[XB_XGEN(b.x)], 1u);
;             asm volatile("s_waitcnt vmcnt(0)" ::: "memory");
;         } else {
;             XB_SPIN(xb_ld(&bar[XB_XGEN(b.x)]) == gen, bar);
.LBB0_476:
	s_and_b32 s24, s26, 0xff
	s_mov_b64 s[22:23], -1
	s_cmp_lg_u32 s24, 0
	s_mov_b64 s[36:37], -1
	s_sleep 0
	s_cbranch_scc0 .LBB0_479
	s_and_b64 vcc, exec, s[36:37]
	s_cbranch_vccz .LBB0_475

; __device__ __forceinline__ unsigned xb_ld(unsigned* p)              { return __hip_atomic_load(p, __ATOMIC_RELAXED, __HIP_MEMORY_SCOPE_AGENT); }
; __device__ __forceinline__ unsigned xb_add(unsigned* p, unsigned v) { return __hip_atomic_fetch_add(p, v, __ATOMIC_RELAXED, __HIP_MEMORY_SCOPE_AGENT); }
; #define XB_SPIN(cond, bar) do { unsigned _sp = 0; while (cond) { __builtin_amdgcn_s_sleep(1); \
;     if ((++_sp & 255u) == 0u) { if (xb_ld(&(bar)[XB_TMO])) break; if (_sp > XB_SPIN_CAP) { atomicAdd(&(bar)[XB_TMO], 1u); break; } } } } while (0)
; __device__ __forceinline__ void xcd_barrier(const XcdBarrier& b) {
;     ...
;             const unsigned og = xb_add(&bar[XB_TOP], 1u);
;             const unsigned tg = og / nx;
;             if (og + 1u == (tg + 1u) * nx) xb_add(&bar[XB_TOPGEN], 1u);
;             else XB_SPIN(xb_ld(&bar[XB_TOPGEN]) == tg, bar);
;             __builtin_amdgcn_fence(__ATOMIC_ACQUIRE, "agent");
;             xb_add(&bar[XB_XGEN(b.x)], 1u);
;             asm volatile("s_waitcnt vmcnt(0)" ::: "memory");
;         } else {
;             XB_SPIN(xb_ld(&bar[XB_XGEN(b.x)]) == gen, bar);
.LBB0_493:
	s_and_b32 s24, s26, 0xff
	s_cmp_lg_u32 s24, 0
	s_mov_b64 s[36:37], -1
	s_sleep 0
	s_cbranch_scc0 .LBB0_496
	s_mov_b64 s[38:39], -1
	s_and_b64 vcc, exec, s[36:37]
	s_cbranch_vccz .LBB0_492

; __device__ __forceinline__ unsigned xb_ld(unsigned* p)              { return __hip_atomic_load(p, __ATOMIC_RELAXED, __HIP_MEMORY_SCOPE_AGENT); }
; __device__ __forceinline__ void xcd_barrier_complete(unsigned* bar, unsigned x, unsigned& nloc, unsigned& nx) {
;     const unsigned G = gridDim.x * gridDim.y * gridDim.z;
;     unsigned sum, cnt, mine, sp = 0u;
;     for (;;) {
;         sum = 0u; cnt = 0u; mine = 0u;
; #pragma unroll
;         for (unsigned j = 0; j < 16; ++j) { const unsigned c = xb_ld(&bar[XB_XCNT(j)]); sum += c; cnt += (c > 0u) ? 1u : 0u; mine = (j == x) ? c : mine; }
;         if (sum == G) break;
;         __builtin_amdgcn_s_sleep(1);
;         if ((++sp & 255u) == 0u) { if (xb_ld(&bar[XB_TMO])) break; if (sp > XB_SPIN_CAP) { atomicAdd(&bar[XB_TMO], 1u); break; } }
;     }
;     nloc = mine > 0u ? mine : 1u; nx = cnt > 0u ? cnt : 1u;
; }
.LBB0_624:
	global_load_dword v17, v18, s[34:35] offset:1024 sc1
	global_load_dword v2, v18, s[34:35] offset:1280 sc1
	global_load_dword v3, v18, s[34:35] offset:1536 sc1
	global_load_dword v4, v18, s[34:35] offset:1792 sc1
	global_load_dword v5, v18, s[34:35] offset:2048 sc1
	global_load_dword v6, v18, s[34:35] offset:2304 sc1
	global_load_dword v7, v18, s[34:35] offset:2560 sc1
	global_load_dword v8, v18, s[34:35] offset:2816 sc1
	global_load_dword v9, v18, s[34:35] offset:3072 sc1
	global_load_dword v10, v18, s[34:35] offset:3328 sc1
	global_load_dword v11, v18, s[34:35] offset:3584 sc1
	global_load_dword v12, v18, s[34:35] offset:3840 sc1
	global_load_dword v13, v18, s[2:3] sc1
	global_load_dword v14, v18, s[4:5] sc1
	global_load_dword v15, v18, s[6:7] sc1
	global_load_dword v16, v18, s[8:9] sc1
	s_mov_b64 s[10:11], -1
	s_mov_b64 s[12:13], -1
	s_waitcnt vmcnt(14)
	v_add_u32_e32 v19, v2, v17
	s_waitcnt vmcnt(13)
	v_add_u32_e32 v19, v19, v3
	s_waitcnt vmcnt(12)
	v_add_u32_e32 v19, v19, v4
	s_waitcnt vmcnt(11)
	v_add_u32_e32 v19, v19, v5
	s_waitcnt vmcnt(10)
	v_add_u32_e32 v19, v19, v6
	s_waitcnt vmcnt(9)
	v_add_u32_e32 v19, v19, v7
	s_waitcnt vmcnt(8)
	v_add_u32_e32 v19, v19, v8
	s_waitcnt vmcnt(7)
	v_add_u32_e32 v19, v19, v9
	s_waitcnt vmcnt(6)
	v_add_u32_e32 v19, v19, v10
	s_waitcnt vmcnt(5)
	v_add_u32_e32 v19, v19, v11
	s_waitcnt vmcnt(4)
	v_add_u32_e32 v19, v19, v12
	s_waitcnt vmcnt(3)
	v_add_u32_e32 v19, v19, v13
	s_waitcnt vmcnt(2)
	v_add_u32_e32 v19, v19, v14
	s_waitcnt vmcnt(1)
	v_add_u32_e32 v19, v19, v15
	s_waitcnt vmcnt(0)
	v_add_u32_e32 v19, v19, v16
	v_cmp_eq_u32_e32 vcc, s16, v19
	s_cbranch_vccnz .LBB0_623
	s_and_b32 s10, s17, 0xff
	s_cmp_eq_u32 s10, 0
	s_mov_b64 s[10:11], -1
	s_mov_b64 s[14:15], -1
	s_sleep 0
	s_cbranch_scc1 .LBB0_628
	s_and_b64 vcc, exec, s[14:15]
	s_cbranch_vccz .LBB0_623

; __device__ __forceinline__ unsigned xb_ld(unsigned* p)              { return __hip_atomic_load(p, __ATOMIC_RELAXED, __HIP_MEMORY_SCOPE_AGENT); }
; __device__ __forceinline__ unsigned xb_add(unsigned* p, unsigned v) { return __hip_atomic_fetch_add(p, v, __ATOMIC_RELAXED, __HIP_MEMORY_SCOPE_AGENT); }
; #define XB_SPIN(cond, bar) do { unsigned _sp = 0; while (cond) { __builtin_amdgcn_s_sleep(1); \
;     if ((++_sp & 255u) == 0u) { if (xb_ld(&(bar)[XB_TMO])) break; if (_sp > XB_SPIN_CAP) { atomicAdd(&(bar)[XB_TMO], 1u); break; } } } } while (0)
; __device__ __forceinline__ void xcd_barrier(const XcdBarrier& b) {
;     ...
;             const unsigned og = xb_add(&bar[XB_TOP], 1u);
;             const unsigned tg = og / nx;
;             if (og + 1u == (tg + 1u) * nx) xb_add(&bar[XB_TOPGEN], 1u);
;             else XB_SPIN(xb_ld(&bar[XB_TOPGEN]) == tg, bar);
;             __builtin_amdgcn_fence(__ATOMIC_ACQUIRE, "agent");
;             xb_add(&bar[XB_XGEN(b.x)], 1u);
;             asm volatile("s_waitcnt vmcnt(0)" ::: "memory");
;         } else {
;             XB_SPIN(xb_ld(&bar[XB_XGEN(b.x)]) == gen, bar);
.LBB0_642:
	s_and_b32 s16, s20, 0xff
	s_mov_b64 s[14:15], -1
	s_cmp_lg_u32 s16, 0
	s_mov_b64 s[18:19], -1
	s_sleep 0
	s_cbranch_scc0 .LBB0_645
	s_and_b64 vcc, exec, s[18:19]
	s_cbranch_vccz .LBB0_641

; __device__ __forceinline__ unsigned xb_ld(unsigned* p)              { return __hip_atomic_load(p, __ATOMIC_RELAXED, __HIP_MEMORY_SCOPE_AGENT); }
; __device__ __forceinline__ unsigned xb_add(unsigned* p, unsigned v) { return __hip_atomic_fetch_add(p, v, __ATOMIC_RELAXED, __HIP_MEMORY_SCOPE_AGENT); }
; #define XB_SPIN(cond, bar) do { unsigned _sp = 0; while (cond) { __builtin_amdgcn_s_sleep(1); \
;     if ((++_sp & 255u) == 0u) { if (xb_ld(&(bar)[XB_TMO])) break; if (_sp > XB_SPIN_CAP) { atomicAdd(&(bar)[XB_TMO], 1u); break; } } } } while (0)
; __device__ __forceinline__ void xcd_barrier(const XcdBarrier& b) {
;     ...
;             const unsigned og = xb_add(&bar[XB_TOP], 1u);
;             const unsigned tg = og / nx;
;             if (og + 1u == (tg + 1u) * nx) xb_add(&bar[XB_TOPGEN], 1u);
;             else XB_SPIN(xb_ld(&bar[XB_TOPGEN]) == tg, bar);
;             __builtin_amdgcn_fence(__ATOMIC_ACQUIRE, "agent");
;             xb_add(&bar[XB_XGEN(b.x)], 1u);
;             asm volatile("s_waitcnt vmcnt(0)" ::: "memory");
;         } else {
;             XB_SPIN(xb_ld(&bar[XB_XGEN(b.x)]) == gen, bar);
.LBB0_659:
	s_and_b32 s16, s22, 0xff
	s_cmp_lg_u32 s16, 0
	s_mov_b64 s[18:19], -1
	s_sleep 0
	s_cbranch_scc0 .LBB0_662
	s_mov_b64 s[20:21], -1
	s_and_b64 vcc, exec, s[18:19]
	s_cbranch_vccz .LBB0_658

; __global__ void __launch_bounds__(512, 2) fwd_kernel(Args a) {
;     ...
;     if (a.ph_hi < 0) cg::this_grid().sync();
.LBB0_2462:
	s_sleep 0
	global_load_dword v2, v0, s[2:3] offset:32 sc1
	s_waitcnt vmcnt(0)
	v_and_b32_e32 v2, 0xffff0000, v2
	v_cmp_ne_u32_e32 vcc, v2, v1
	s_or_b64 s[4:5], vcc, s[4:5]
	s_andn2_b64 exec, exec, s[4:5]
	s_cbranch_execnz .LBB0_2462
